# NSA unit prologue: q and gate loads issued at the top of the unit so their round trip overlaps the compressed K/V staging loops
# baseline (speedup 1.0000x reference)
; #define LAS __attribute__((address_space(3)))
; DI unsigned pk2(float lo, float hi) { const f32x2 v = {lo, hi}; const hwbf16x2 b = __builtin_convertvector(v, hwbf16x2); return __builtin_bit_cast(unsigned, b); }
; DI float fsigmoid(float v) { return frcp(1.f + __expf(-v)); }
; DI void nsa_unit(const Params& p, LAS unsigned char* lds, unsigned char* ldsg, int bg, int qt, int tid) {
;     ...
;     const int lane = tid & 63, w = __builtin_amdgcn_readfirstlane(tid >> 6), c = lane & 31, hi = lane >> 5;
;     const int b = bg >> 1, g = bg & 1, q0 = qt * 32;
;     const int head = c & 7, qi = c >> 3, tw0 = q0 + 4 * w, t = tw0 + qi, hh = g * 8 + head;
;     const size_t tokb = (size_t)b * S_, tok = tokb + t;
;     const float sc2 = 0.125f * LOG2E, slope2 = exp2f(-0.5f * (float)(hh + 1)) * LOG2E;
;     LAS unsigned* SEL = (LAS unsigned*)(lds + NSA_SEL);
;     LAS unsigned* UNI = (LAS unsigned*)(lds + NSA_UNI);
;     LAS int* NL = (LAS int*)(lds + NSA_NL);
;     LAS int* LIST = (LAS int*)(lds + NSA_LIST);
;     LAS float* IMPw = (LAS float*)(lds + NSA_IMP + w * 2048);
;     __syncthreads();
;     const int nct = (q0 / 16 + 1 + 31) >> 5;
;     ...
;     { const bf16_t* qp = PROJ + tok * NPROJ + 832 + hh * 64 + 8 * hi;
; #pragma unroll
;       for (int st = 0; st < 4; ++st) {
;           const u32x4 raw = *(const u32x4*)(qp + 16 * st); u32x4 sc;
;           sc.x = pk2(bflo(raw.x) * sc2, bfhi(raw.x) * sc2); sc.y = pk2(bflo(raw.y) * sc2, bfhi(raw.y) * sc2);
;           sc.z = pk2(bflo(raw.z) * sc2, bfhi(raw.z) * sc2); sc.w = pk2(bflo(raw.w) * sc2, bfhi(raw.w) * sc2);
;           qf[st] = __builtin_bit_cast(bf16x8, sc); } }
;     const bf16_t* gp = PROJ + tok * NPROJ + 2624 + hh * 3;
;     const float gate_c = fsigmoid(bf2f(gp[0])), gate_s = fsigmoid(bf2f(gp[1])), gate_w = fsigmoid(bf2f(gp[2]));
.LBB0_691:
	v_mov_b32_e32 v66, v167
	s_add_i32 s2, s12, s54
	s_and_b32 s87, s2, 1
	v_and_b32_e32 v108, 7, v66
	v_lshl_or_b32 v19, s87, 3, v108
	s_and_b32 s48, s2, 7
	s_lshl_b32 s2, s12, 2
	v_add_u32_e32 v0, 1, v19
	s_andn2_b32 s2, s2, 31
	s_bitcmp1_b32 s12, 8
	s_cselect_b32 s3, 0x3e0, 0
	s_xor_b32 s2, s2, s3
	v_cvt_f32_ubyte0_e32 v22, v0
	s_sub_i32 s57, 0x1fe0, s2
	v_mul_f32_e32 v0, -0.5, v22
	s_mov_b32 s2, 0xc2fc0000
	v_cmp_gt_f32_e32 vcc, s2, v0
	s_lshr_b32 s2, s57, 4
	s_add_i32 s2, s2, 32
	s_lshr_b32 s16, s2, 5
	s_and_b32 s56, s69, 0xffffffe0
	s_xor_b32 s56, s56, s3
	s_lshl_b32 s19, s16, 8
	s_sub_i32 s18, 0x1fe0, s56
	v_readfirstlane_b32 s88, v66
	s_ashr_i32 s98, s88, 6
	s_lshl_b32 s98, s98, 2
	v_bfe_u32 v236, v66, 3, 2
	s_add_i32 s98, s98, s57
	v_or_b32_e32 v238, s98, v236
	s_lshl_b32 s99, s48, 12
	s_and_b32 s100, s99, 0x6000
	s_mov_b32 s101, s67
	v_ashrrev_i32_e32 v239, 31, v238
	v_lshl_add_u64 v[238:239], v[238:239], 0, s[100:101]
	v_mov_b64_e32 v[240:241], s[44:45]
	v_mad_u64_u32 v[242:243], s[98:99], v238, s95, v[240:241]
	v_mad_i32_i24 v243, v239, s95, v243
	v_lshlrev_b32_e32 v240, 7, v19
	v_mov_b32_e32 v241, 0
	v_lshl_add_u64 v[244:245], v[242:243], 0, v[240:241]
	v_bfe_u32 v240, v66, 5, 1
	v_lshlrev_b32_e32 v240, 4, v240
	v_lshl_add_u64 v[244:245], v[244:245], 0, v[240:241]
	global_load_dwordx4 v[212:215], v[244:245], off offset:1664
	global_load_dwordx4 v[216:219], v[244:245], off offset:1696
	global_load_dwordx4 v[220:223], v[244:245], off offset:1728
	global_load_dwordx4 v[224:227], v[244:245], off offset:1760
	v_mul_u32_u24_e32 v240, 3, v19
	v_lshlrev_b32_e32 v240, 1, v240
	v_lshl_add_u64 v[242:243], v[242:243], 0, v[240:241]
	s_mov_b64 s[98:99], 0x1480
	v_lshl_add_u64 v[246:247], v[242:243], 0, s[98:99]
	s_mov_b32 s100, s92
	s_mov_b32 s101, 0
	v_lshl_add_u64 v[242:243], v[242:243], 0, s[100:101]
	global_load_dword v228, v[242:243], off offset:1152
	global_load_ushort v229, v[246:247], off offset:4
	v_cmp_gt_i32_e64 s[2:3], s19, v66
	s_barrier
	s_and_saveexec_b64 s[10:11], s[2:3]
	s_cbranch_execz .LBB0_720
	v_lshlrev_b32_e32 v23, 4, v66
	v_lshlrev_b32_e32 v18, 3, v66
	s_lshl_b32 s17, s48, 9
	s_mov_b64 s[8:9], 0
	v_mov_b32_e32 v24, v18
	v_mov_b32_e32 v25, v23
	v_mov_b32_e32 v26, v66
	s_branch .LBB0_694

; DI unsigned pk2(float lo, float hi) { const f32x2 v = {lo, hi}; const hwbf16x2 b = __builtin_convertvector(v, hwbf16x2); return __builtin_bit_cast(unsigned, b); }
; DI float fsigmoid(float v) { return frcp(1.f + __expf(-v)); }
; DI void nsa_unit(const Params& p, LAS unsigned char* lds, unsigned char* ldsg, int bg, int qt, int tid) {
;     ...
;     if (tid < 4) UNI[tid] = 0u;
;     bf16x8 qf[4];
;     { const bf16_t* qp = PROJ + tok * NPROJ + 832 + hh * 64 + 8 * hi;
; #pragma unroll
;       for (int st = 0; st < 4; ++st) {
;           const u32x4 raw = *(const u32x4*)(qp + 16 * st); u32x4 sc;
;           sc.x = pk2(bflo(raw.x) * sc2, bfhi(raw.x) * sc2); sc.y = pk2(bflo(raw.y) * sc2, bfhi(raw.y) * sc2);
;           sc.z = pk2(bflo(raw.z) * sc2, bfhi(raw.z) * sc2); sc.w = pk2(bflo(raw.w) * sc2, bfhi(raw.w) * sc2);
;           qf[st] = __builtin_bit_cast(bf16x8, sc); } }
;     const bf16_t* gp = PROJ + tok * NPROJ + 2624 + hh * 3;
;     const float gate_c = fsigmoid(bf2f(gp[0])), gate_s = fsigmoid(bf2f(gp[1])), gate_w = fsigmoid(bf2f(gp[2]));
;     __syncthreads();
;     ...
;         const int cwm = (tw0 + 3 >= 31) ? ((tw0 + 3 - 31) >> 4) : -1;
;         const int ntw = (cwm >= 0) ? (cwm >> 5) + 1 : 0;
;         const float slope16 = 16.f * slope2;
;         float m1 = -1e20f, l1 = 0.f;
.LBB0_720:
	s_or_b64 exec, exec, s[10:11]
	v_cndmask_b32_e32 v0, 0, v162, vcc
	v_fmac_f32_e32 v0, -0.5, v22
	v_exp_f32_e32 v0, v0
	v_cndmask_b32_e32 v2, 0, v163, vcc
	s_max_i32 s84, s18, 0x1ff
	v_cmp_gt_i32_e32 vcc, 4, v66
	v_ldexp_f32 v12, v0, v2
	s_and_saveexec_b64 s[2:3], vcc
	v_lshl_add_u32 v0, v66, 2, 0
	v_add_u32_e32 v0, 0x26600, v0
	ds_write_b32 v0, v1
	s_or_b64 exec, exec, s[2:3]
	s_ashr_i32 s38, s88, 6
	s_lshl_b32 s49, s38, 2
	v_bfe_u32 v67, v66, 3, 2
	s_add_i32 s40, s49, s57
	v_or_b32_e32 v150, s40, v67
	s_lshl_b32 s2, s48, 12
	s_and_b32 s66, s2, 0x6000
	v_ashrrev_i32_e32 v151, 31, v150
	v_lshl_add_u64 v[148:149], v[150:151], 0, s[66:67]
	v_mov_b64_e32 v[2:3], s[44:45]
	v_mad_u64_u32 v[10:11], s[2:3], v148, s95, v[2:3]
	v_bfe_u32 v114, v66, 5, 1
	v_mad_i32_i24 v11, v149, s95, v11
	v_lshlrev_b32_e32 v0, 7, v19
	v_lshl_add_u64 v[2:3], v[10:11], 0, v[0:1]
	v_lshlrev_b32_e32 v0, 4, v114
	v_lshl_add_u64 v[20:21], v[2:3], 0, v[0:1]
	s_waitcnt vmcnt(0)
	v_mov_b32_e32 v2, v212
	v_mov_b32_e32 v3, v213
	v_mov_b32_e32 v4, v214
	v_mov_b32_e32 v5, v215
	v_mov_b32_e32 v6, v216
	v_mov_b32_e32 v7, v217
	v_mov_b32_e32 v8, v218
	v_mov_b32_e32 v9, v219
	v_mov_b32_e32 v14, v220
	v_mov_b32_e32 v15, v221
	v_mov_b32_e32 v16, v222
	v_mov_b32_e32 v17, v223
	s_nop 0
	v_mov_b32_e32 v20, v224
	v_mov_b32_e32 v21, v225
	v_mov_b32_e32 v22, v226
	v_mov_b32_e32 v23, v227
	v_mul_f32_e32 v152, 0x3fb8aa3b, v12
	v_mul_u32_u24_e32 v12, 3, v19
	v_mov_b32_e32 v13, v1
	v_lshlrev_b32_e32 v12, 1, v12
	s_mov_b64 s[2:3], 0x1480
	v_lshl_add_u64 v[10:11], v[10:11], 0, v[12:13]
	v_lshl_add_u64 v[12:13], v[10:11], 0, s[2:3]
	v_add_co_u32_e32 v10, vcc, s92, v10
	s_sub_i32 s2, s40, 28
	s_nop 0
	v_addc_co_u32_e32 v11, vcc, 0, v11, vcc
	v_mov_b32_e32 v155, v228
	v_mov_b32_e32 v151, v229
	s_or_b32 s55, s40, 3
	s_ashr_i32 s2, s2, 4
	s_cmp_gt_i32 s55, 30
	s_cselect_b32 s2, s2, -1
	s_ashr_i32 s3, s2, 5
	s_add_i32 s3, s3, 1
	s_cmp_gt_i32 s2, -1
	s_cselect_b32 s85, s3, 0
	v_and_b32_e32 v68, 31, v66
	s_cmp_gt_i32 s85, 0
	v_add_u32_e32 v115, s49, v67
	v_mul_f32_e32 v64, 0x41800000, v152
	s_cselect_b64 s[36:37], -1, 0
	s_cmp_lt_i32 s85, 1
	v_lshlrev_b32_e32 v18, 6, v114
	v_mul_u32_u24_e32 v171, 0x90, v68
	s_waitcnt lgkmcnt(0)
	s_barrier
	s_waitcnt vmcnt(5)
	v_lshlrev_b32_e32 v10, 16, v2
	v_and_b32_e32 v11, 0xffff0000, v2
	v_lshlrev_b32_e32 v2, 16, v3
	v_and_b32_e32 v3, 0xffff0000, v3
	v_pk_mul_f32 v[2:3], v[2:3], s[68:69] op_sel_hi:[1,0]
	v_lshlrev_b32_e32 v12, 16, v4
	v_cvt_pk_bf16_f32 v129, v2, v3
	s_waitcnt vmcnt(2)
	v_lshlrev_b32_e32 v2, 16, v22
	v_and_b32_e32 v3, 0xffff0000, v22
	v_pk_mul_f32 v[2:3], v[2:3], s[68:69] op_sel_hi:[1,0]
	v_and_b32_e32 v13, 0xffff0000, v4
	v_lshlrev_b32_e32 v4, 16, v5
	v_and_b32_e32 v5, 0xffff0000, v5
	v_lshlrev_b32_e32 v24, 16, v6
	v_and_b32_e32 v25, 0xffff0000, v6
	v_lshlrev_b32_e32 v6, 16, v7
	v_and_b32_e32 v7, 0xffff0000, v7
	v_lshlrev_b32_e32 v26, 16, v8
	v_and_b32_e32 v27, 0xffff0000, v8
	v_lshlrev_b32_e32 v8, 16, v9
	v_and_b32_e32 v9, 0xffff0000, v9
	v_lshlrev_b32_e32 v28, 16, v14
	v_and_b32_e32 v29, 0xffff0000, v14
	v_lshlrev_b32_e32 v14, 16, v15
	v_and_b32_e32 v15, 0xffff0000, v15
	v_lshlrev_b32_e32 v30, 16, v16
	v_and_b32_e32 v31, 0xffff0000, v16
	v_lshlrev_b32_e32 v16, 16, v17
	v_and_b32_e32 v17, 0xffff0000, v17
	v_lshlrev_b32_e32 v32, 16, v20
	v_and_b32_e32 v33, 0xffff0000, v20
	v_lshlrev_b32_e32 v20, 16, v21
	v_and_b32_e32 v21, 0xffff0000, v21
	v_cvt_pk_bf16_f32 v142, v2, v3
	v_lshlrev_b32_e32 v2, 16, v23
	v_and_b32_e32 v3, 0xffff0000, v23
	v_pk_mul_f32 v[10:11], v[10:11], s[68:69] op_sel_hi:[1,0]
	v_pk_mul_f32 v[12:13], v[12:13], s[68:69] op_sel_hi:[1,0]
	v_pk_mul_f32 v[4:5], v[4:5], s[68:69] op_sel_hi:[1,0]
	v_pk_mul_f32 v[24:25], v[24:25], s[68:69] op_sel_hi:[1,0]
	v_pk_mul_f32 v[6:7], v[6:7], s[68:69] op_sel_hi:[1,0]
	v_pk_mul_f32 v[26:27], v[26:27], s[68:69] op_sel_hi:[1,0]
	v_pk_mul_f32 v[8:9], v[8:9], s[68:69] op_sel_hi:[1,0]
	v_pk_mul_f32 v[28:29], v[28:29], s[68:69] op_sel_hi:[1,0]
	v_pk_mul_f32 v[14:15], v[14:15], s[68:69] op_sel_hi:[1,0]
	v_pk_mul_f32 v[30:31], v[30:31], s[68:69] op_sel_hi:[1,0]
	v_pk_mul_f32 v[16:17], v[16:17], s[68:69] op_sel_hi:[1,0]
	v_pk_mul_f32 v[32:33], v[32:33], s[68:69] op_sel_hi:[1,0]
	v_pk_mul_f32 v[20:21], v[20:21], s[68:69] op_sel_hi:[1,0]
	v_pk_mul_f32 v[2:3], v[2:3], s[68:69] op_sel_hi:[1,0]
	v_cvt_pk_bf16_f32 v128, v10, v11
	v_cvt_pk_bf16_f32 v130, v12, v13
	v_cvt_pk_bf16_f32 v131, v4, v5
	v_cvt_pk_bf16_f32 v132, v24, v25
	v_cvt_pk_bf16_f32 v133, v6, v7
	v_cvt_pk_bf16_f32 v134, v26, v27
	v_cvt_pk_bf16_f32 v135, v8, v9
	v_cvt_pk_bf16_f32 v136, v28, v29
	v_cvt_pk_bf16_f32 v137, v14, v15
	v_cvt_pk_bf16_f32 v138, v30, v31
	v_cvt_pk_bf16_f32 v139, v16, v17
	v_cvt_pk_bf16_f32 v140, v32, v33
	v_cvt_pk_bf16_f32 v141, v20, v21
	v_cvt_pk_bf16_f32 v143, v2, v3
	v_subrev_u32_e32 v20, s56, v115
	s_cbranch_scc1 .LBB0_728
	v_sub_u32_e32 v2, v20, v18
	v_mov_b32_e32 v65, v64
	v_add3_u32 v21, v171, v0, 0
	v_add_u32_e32 v22, 0x1fc1, v2
	v_mov_b32_e32 v23, 0
	v_mov_b32_e32 v24, 0xe0ad78ec
	s_movk_i32 s39, 0x20f
	s_mov_b32 s46, s85
